# POST transposing region: next block's four row loads prefetched before the current block's barrier/store section (two register sets)
# baseline (speedup 1.0000x reference)
; #define LAS __attribute__((address_space(3)))
; __device__ __forceinline__ int perm16(int row) { const int q = (row >> 2) & 3; const int q2 = (q == 1) ? 2 : (q == 2 ? 1 : q); return (row & ~15) | (q2 << 2) | (row & 3); }
; template <bool PERMK, class F> __device__ __forceinline__ void post_transpose(const bf16_t* px, int c0, LAS unsigned short* Lt, int tid, F&& destrow) {
;     u32x4 v[4];
; #pragma unroll
;     for (int j = 0; j < 4; ++j) { const int c = tid + j * NTHREADS; v[j] = *(const u32x4*)(px + (size_t)(c >> 4) * NIN + c0 + (c & 15) * 8); }
; #pragma unroll
;     for (int j = 0; j < 4; ++j) {
;         const int c = tid + j * NTHREADS, row = c >> 4, ch = c & 15;
;         const int pr = (PERMK ? perm16(row) : row) ^ (ch << 3);
;         LAS unsigned short* d = Lt + (ch * 8) * 136 + pr;
;         d[0] = (unsigned short)(v[j].x & 0xffff); d[136] = (unsigned short)(v[j].x >> 16); d[2 * 136] = (unsigned short)(v[j].y & 0xffff); d[3 * 136] = (unsigned short)(v[j].y >> 16);
;         d[4 * 136] = (unsigned short)(v[j].z & 0xffff); d[5 * 136] = (unsigned short)(v[j].z >> 16); d[6 * 136] = (unsigned short)(v[j].w & 0xffff); d[7 * 136] = (unsigned short)(v[j].w >> 16);
;     }
;     __syncthreads();
; #pragma unroll
;     for (int j = 0; j < 4; ++j) {
;         const int c = tid + j * NTHREADS, col = c >> 4, ch = c & 15;
;         const u32x4 w = *(const LAS u32x4*)(Lt + col * 136 + ((ch * 8) ^ (((col >> 3) & 15) << 3)));
;         *(u32x4*)(destrow(col) + ch * 8) = w;
;     }
.LBB0_360:
	s_and_b64 vcc, exec, s[0:1]
	s_cbranch_vccz .LBB0_377
	v_lshlrev_b32_e32 v186, 1, v48
	v_lshl_add_u64 v[8:9], s[46:47], 0, v[186:187]
	v_lshl_add_u64 v[14:15], v[8:9], 0, v[50:51]
	global_load_dwordx4 v[160:163], v[14:15], off offset:1536
	v_lshl_add_u64 v[12:13], v[8:9], 0, v[52:53]
	v_lshl_add_u64 v[10:11], v[8:9], 0, v[54:55]
	v_lshl_add_u64 v[8:9], v[8:9], 0, v[56:57]
	global_load_dwordx4 v[164:167], v[12:13], off offset:1536
	global_load_dwordx4 v[168:171], v[10:11], off offset:1536
	global_load_dwordx4 v[172:175], v[8:9], off offset:1536
	s_lshl_b32 s76, s9, 1
	s_lshl_b32 s10, s8, 8
	v_lshl_add_u64 v[6:7], v[60:61], 0, s[76:77]
	v_lshl_add_u64 v[4:5], v[64:65], 0, s[76:77]
	v_lshl_add_u64 v[2:3], v[68:69], 0, s[76:77]
	v_lshl_add_u64 v[0:1], v[72:73], 0, s[76:77]
	s_mov_b64 s[0:1], -1
	s_and_b64 vcc, exec, s[94:95]
	s_waitcnt vmcnt(3)
	ds_write_b16 v67, v160
	ds_write_b16_d16_hi v67, v160 offset:272
	ds_write_b16 v67, v161 offset:544
	ds_write_b16_d16_hi v67, v161 offset:816
	ds_write_b16 v67, v162 offset:1088
	ds_write_b16_d16_hi v67, v162 offset:1360
	ds_write_b16 v67, v163 offset:1632
	ds_write_b16_d16_hi v67, v163 offset:1904
	s_waitcnt vmcnt(2)
	ds_write_b16 v71, v164
	ds_write_b16_d16_hi v71, v164 offset:272
	ds_write_b16 v71, v165 offset:544
	ds_write_b16_d16_hi v71, v165 offset:816
	ds_write_b16 v71, v166 offset:1088
	ds_write_b16_d16_hi v71, v166 offset:1360
	ds_write_b16 v71, v167 offset:1632
	ds_write_b16_d16_hi v71, v167 offset:1904
	s_waitcnt vmcnt(1)
	ds_write_b16 v77, v168
	ds_write_b16_d16_hi v77, v168 offset:272
	ds_write_b16 v77, v169 offset:544
	ds_write_b16_d16_hi v77, v169 offset:816
	ds_write_b16 v77, v170 offset:1088
	ds_write_b16_d16_hi v77, v170 offset:1360
	ds_write_b16 v77, v171 offset:1632
	ds_write_b16_d16_hi v77, v171 offset:1904
	s_waitcnt vmcnt(0)
	ds_write_b16 v106, v172
	ds_write_b16_d16_hi v106, v172 offset:272
	ds_write_b16 v106, v173 offset:544
	ds_write_b16_d16_hi v106, v173 offset:816
	ds_write_b16 v106, v174 offset:1088
	ds_write_b16_d16_hi v106, v174 offset:1360
	ds_write_b16 v106, v175 offset:1632
	ds_write_b16_d16_hi v106, v175 offset:1904
	global_load_dwordx4 v[192:195], v[14:15], off offset:1792
	global_load_dwordx4 v[196:199], v[12:13], off offset:1792
	global_load_dwordx4 v[200:203], v[10:11], off offset:1792
	global_load_dwordx4 v[204:207], v[8:9], off offset:1792
	s_waitcnt lgkmcnt(0)
	s_cbranch_vccz .LBB0_363
	s_barrier
	ds_read_b128 v[16:19], v107
	v_or_b32_e32 v186, s10, v58
	v_lshlrev_b64 v[20:21], 10, v[186:187]
	v_lshl_add_u64 v[20:21], v[6:7], 0, v[20:21]
	v_or_b32_e32 v186, s10, v62
	s_waitcnt lgkmcnt(0)
	global_store_dwordx4 v[20:21], v[16:19], off
	ds_read_b128 v[16:19], v108
	v_lshlrev_b64 v[20:21], 10, v[186:187]
	v_lshl_add_u64 v[20:21], v[4:5], 0, v[20:21]
	v_or_b32_e32 v186, s10, v66
	s_mov_b64 s[0:1], 0
	s_waitcnt lgkmcnt(0)
	global_store_dwordx4 v[20:21], v[16:19], off
	ds_read_b128 v[16:19], v109
	v_lshlrev_b64 v[20:21], 10, v[186:187]
	v_lshl_add_u64 v[20:21], v[2:3], 0, v[20:21]
	v_or_b32_e32 v186, s10, v70
	s_waitcnt lgkmcnt(0)
	global_store_dwordx4 v[20:21], v[16:19], off
	ds_read_b128 v[16:19], v110
	v_lshlrev_b64 v[20:21], 10, v[186:187]
	v_lshl_add_u64 v[20:21], v[0:1], 0, v[20:21]
	s_waitcnt lgkmcnt(0)
	global_store_dwordx4 v[20:21], v[16:19], off
	s_barrier

; #define LAS __attribute__((address_space(3)))
; __device__ __forceinline__ int perm16(int row) { const int q = (row >> 2) & 3; const int q2 = (q == 1) ? 2 : (q == 2 ? 1 : q); return (row & ~15) | (q2 << 2) | (row & 3); }
; template <bool PERMK, class F> __device__ __forceinline__ void post_transpose(const bf16_t* px, int c0, LAS unsigned short* Lt, int tid, F&& destrow) {
;     u32x4 v[4];
; #pragma unroll
;     for (int j = 0; j < 4; ++j) { const int c = tid + j * NTHREADS; v[j] = *(const u32x4*)(px + (size_t)(c >> 4) * NIN + c0 + (c & 15) * 8); }
; #pragma unroll
;     for (int j = 0; j < 4; ++j) {
;         const int c = tid + j * NTHREADS, row = c >> 4, ch = c & 15;
;         const int pr = (PERMK ? perm16(row) : row) ^ (ch << 3);
;         LAS unsigned short* d = Lt + (ch * 8) * 136 + pr;
;         d[0] = (unsigned short)(v[j].x & 0xffff); d[136] = (unsigned short)(v[j].x >> 16); d[2 * 136] = (unsigned short)(v[j].y & 0xffff); d[3 * 136] = (unsigned short)(v[j].y >> 16);
;         d[4 * 136] = (unsigned short)(v[j].z & 0xffff); d[5 * 136] = (unsigned short)(v[j].z >> 16); d[6 * 136] = (unsigned short)(v[j].w & 0xffff); d[7 * 136] = (unsigned short)(v[j].w >> 16);
;     }
;     __syncthreads();
; #pragma unroll
;     for (int j = 0; j < 4; ++j) {
;         const int c = tid + j * NTHREADS, col = c >> 4, ch = c & 15;
;         const u32x4 w = *(const LAS u32x4*)(Lt + col * 136 + ((ch * 8) ^ (((col >> 3) & 15) << 3)));
;         *(u32x4*)(destrow(col) + ch * 8) = w;
;     }
.LBB0_365:
	v_cndmask_b32_e64 v19, 0, 1, s[94:95]
	s_mov_b64 s[4:5], -1
	v_cmp_ne_u32_e64 s[0:1], 1, v19
	s_andn2_b64 vcc, exec, s[94:95]
	s_waitcnt vmcnt(4)
	ds_write_b16 v67, v192
	ds_write_b16_d16_hi v67, v192 offset:272
	ds_write_b16 v67, v193 offset:544
	ds_write_b16_d16_hi v67, v193 offset:816
	ds_write_b16 v67, v194 offset:1088
	ds_write_b16_d16_hi v67, v194 offset:1360
	ds_write_b16 v67, v195 offset:1632
	ds_write_b16_d16_hi v67, v195 offset:1904
	ds_write_b16 v71, v196
	ds_write_b16_d16_hi v71, v196 offset:272
	ds_write_b16 v71, v197 offset:544
	ds_write_b16_d16_hi v71, v197 offset:816
	ds_write_b16 v71, v198 offset:1088
	ds_write_b16_d16_hi v71, v198 offset:1360
	ds_write_b16 v71, v199 offset:1632
	ds_write_b16_d16_hi v71, v199 offset:1904
	ds_write_b16 v77, v200
	ds_write_b16_d16_hi v77, v200 offset:272
	ds_write_b16 v77, v201 offset:544
	ds_write_b16_d16_hi v77, v201 offset:816
	ds_write_b16 v77, v202 offset:1088
	ds_write_b16_d16_hi v77, v202 offset:1360
	ds_write_b16 v77, v203 offset:1632
	ds_write_b16_d16_hi v77, v203 offset:1904
	ds_write_b16 v106, v204
	ds_write_b16_d16_hi v106, v204 offset:272
	ds_write_b16 v106, v205 offset:544
	ds_write_b16_d16_hi v106, v205 offset:816
	ds_write_b16 v106, v206 offset:1088
	ds_write_b16_d16_hi v106, v206 offset:1360
	ds_write_b16 v106, v207 offset:1632
	ds_write_b16_d16_hi v106, v207 offset:1904
	global_load_dwordx4 v[160:163], v[14:15], off offset:2048
	global_load_dwordx4 v[164:167], v[12:13], off offset:2048
	global_load_dwordx4 v[168:171], v[10:11], off offset:2048
	global_load_dwordx4 v[172:175], v[8:9], off offset:2048
	s_waitcnt lgkmcnt(0)
	s_cbranch_vccnz .LBB0_367
	s_barrier
	ds_read_b128 v[26:29], v107
	s_or_b32 s4, s10, 64
	v_or_b32_e32 v186, s4, v58
	v_lshlrev_b64 v[30:31], 10, v[186:187]
	v_lshl_add_u64 v[30:31], v[6:7], 0, v[30:31]
	s_waitcnt lgkmcnt(0)
	global_store_dwordx4 v[30:31], v[26:29], off
	ds_read_b128 v[26:29], v108
	v_or_b32_e32 v186, s4, v62
	v_lshlrev_b64 v[30:31], 10, v[186:187]
	v_lshl_add_u64 v[30:31], v[4:5], 0, v[30:31]
	v_or_b32_e32 v186, s4, v66
	s_waitcnt lgkmcnt(0)
	global_store_dwordx4 v[30:31], v[26:29], off
	ds_read_b128 v[26:29], v109
	v_lshlrev_b64 v[30:31], 10, v[186:187]
	v_lshl_add_u64 v[30:31], v[2:3], 0, v[30:31]
	v_or_b32_e32 v186, s4, v70
	s_mov_b64 s[4:5], 0
	s_waitcnt lgkmcnt(0)
	global_store_dwordx4 v[30:31], v[26:29], off
	ds_read_b128 v[26:29], v110
	v_lshlrev_b64 v[30:31], 10, v[186:187]
	v_lshl_add_u64 v[30:31], v[0:1], 0, v[30:31]
	s_waitcnt lgkmcnt(0)
	global_store_dwordx4 v[30:31], v[26:29], off
	s_barrier

; #define LAS __attribute__((address_space(3)))
; __device__ __forceinline__ int perm16(int row) { const int q = (row >> 2) & 3; const int q2 = (q == 1) ? 2 : (q == 2 ? 1 : q); return (row & ~15) | (q2 << 2) | (row & 3); }
; template <bool PERMK, class F> __device__ __forceinline__ void post_transpose(const bf16_t* px, int c0, LAS unsigned short* Lt, int tid, F&& destrow) {
;     u32x4 v[4];
; #pragma unroll
;     for (int j = 0; j < 4; ++j) { const int c = tid + j * NTHREADS; v[j] = *(const u32x4*)(px + (size_t)(c >> 4) * NIN + c0 + (c & 15) * 8); }
; #pragma unroll
;     for (int j = 0; j < 4; ++j) {
;         const int c = tid + j * NTHREADS, row = c >> 4, ch = c & 15;
;         const int pr = (PERMK ? perm16(row) : row) ^ (ch << 3);
;         LAS unsigned short* d = Lt + (ch * 8) * 136 + pr;
;         d[0] = (unsigned short)(v[j].x & 0xffff); d[136] = (unsigned short)(v[j].x >> 16); d[2 * 136] = (unsigned short)(v[j].y & 0xffff); d[3 * 136] = (unsigned short)(v[j].y >> 16);
;         d[4 * 136] = (unsigned short)(v[j].z & 0xffff); d[5 * 136] = (unsigned short)(v[j].z >> 16); d[6 * 136] = (unsigned short)(v[j].w & 0xffff); d[7 * 136] = (unsigned short)(v[j].w >> 16);
;     }
;     __syncthreads();
; #pragma unroll
;     for (int j = 0; j < 4; ++j) {
;         const int c = tid + j * NTHREADS, col = c >> 4, ch = c & 15;
;         const u32x4 w = *(const LAS u32x4*)(Lt + col * 136 + ((ch * 8) ^ (((col >> 3) & 15) << 3)));
;         *(u32x4*)(destrow(col) + ch * 8) = w;
;     }
.LBB0_369:
	s_mov_b64 s[4:5], -1
	s_and_b64 vcc, exec, s[0:1]
	s_waitcnt vmcnt(4)
	ds_write_b16 v67, v160
	ds_write_b16_d16_hi v67, v160 offset:272
	ds_write_b16 v67, v161 offset:544
	ds_write_b16_d16_hi v67, v161 offset:816
	ds_write_b16 v67, v162 offset:1088
	ds_write_b16_d16_hi v67, v162 offset:1360
	ds_write_b16 v67, v163 offset:1632
	ds_write_b16_d16_hi v67, v163 offset:1904
	ds_write_b16 v71, v164
	ds_write_b16_d16_hi v71, v164 offset:272
	ds_write_b16 v71, v165 offset:544
	ds_write_b16_d16_hi v71, v165 offset:816
	ds_write_b16 v71, v166 offset:1088
	ds_write_b16_d16_hi v71, v166 offset:1360
	ds_write_b16 v71, v167 offset:1632
	ds_write_b16_d16_hi v71, v167 offset:1904
	ds_write_b16 v77, v168
	ds_write_b16_d16_hi v77, v168 offset:272
	ds_write_b16 v77, v169 offset:544
	ds_write_b16_d16_hi v77, v169 offset:816
	ds_write_b16 v77, v170 offset:1088
	ds_write_b16_d16_hi v77, v170 offset:1360
	ds_write_b16 v77, v171 offset:1632
	ds_write_b16_d16_hi v77, v171 offset:1904
	ds_write_b16 v106, v172
	ds_write_b16_d16_hi v106, v172 offset:272
	ds_write_b16 v106, v173 offset:544
	ds_write_b16_d16_hi v106, v173 offset:816
	ds_write_b16 v106, v174 offset:1088
	ds_write_b16_d16_hi v106, v174 offset:1360
	ds_write_b16 v106, v175 offset:1632
	ds_write_b16_d16_hi v106, v175 offset:1904
	global_load_dwordx4 v[192:195], v[14:15], off offset:2304
	global_load_dwordx4 v[196:199], v[12:13], off offset:2304
	global_load_dwordx4 v[200:203], v[10:11], off offset:2304
	global_load_dwordx4 v[204:207], v[8:9], off offset:2304
	s_waitcnt lgkmcnt(0)
	s_cbranch_vccnz .LBB0_371
	s_barrier
	ds_read_b128 v[26:29], v107
	s_or_b32 s4, s10, 0x80
	v_or_b32_e32 v186, s4, v58
	v_lshlrev_b64 v[30:31], 10, v[186:187]
	v_lshl_add_u64 v[30:31], v[6:7], 0, v[30:31]
	s_waitcnt lgkmcnt(0)
	global_store_dwordx4 v[30:31], v[26:29], off
	ds_read_b128 v[26:29], v108
	v_or_b32_e32 v186, s4, v62
	v_lshlrev_b64 v[30:31], 10, v[186:187]
	v_lshl_add_u64 v[30:31], v[4:5], 0, v[30:31]
	v_or_b32_e32 v186, s4, v66
	s_waitcnt lgkmcnt(0)
	global_store_dwordx4 v[30:31], v[26:29], off
	ds_read_b128 v[26:29], v109
	v_lshlrev_b64 v[30:31], 10, v[186:187]
	v_lshl_add_u64 v[30:31], v[2:3], 0, v[30:31]
	v_or_b32_e32 v186, s4, v70
	s_mov_b64 s[4:5], 0
	s_waitcnt lgkmcnt(0)
	global_store_dwordx4 v[30:31], v[26:29], off
	ds_read_b128 v[26:29], v110
	v_lshlrev_b64 v[30:31], 10, v[186:187]
	v_lshl_add_u64 v[30:31], v[0:1], 0, v[30:31]
	s_waitcnt lgkmcnt(0)
	global_store_dwordx4 v[30:31], v[26:29], off
	s_barrier

; #define LAS __attribute__((address_space(3)))
; __device__ __forceinline__ int perm16(int row) { const int q = (row >> 2) & 3; const int q2 = (q == 1) ? 2 : (q == 2 ? 1 : q); return (row & ~15) | (q2 << 2) | (row & 3); }
; template <bool PERMK, class F> __device__ __forceinline__ void post_transpose(const bf16_t* px, int c0, LAS unsigned short* Lt, int tid, F&& destrow) {
;     u32x4 v[4];
; #pragma unroll
;     for (int j = 0; j < 4; ++j) { const int c = tid + j * NTHREADS; v[j] = *(const u32x4*)(px + (size_t)(c >> 4) * NIN + c0 + (c & 15) * 8); }
; #pragma unroll
;     for (int j = 0; j < 4; ++j) {
;         const int c = tid + j * NTHREADS, row = c >> 4, ch = c & 15;
;         const int pr = (PERMK ? perm16(row) : row) ^ (ch << 3);
;         LAS unsigned short* d = Lt + (ch * 8) * 136 + pr;
;         d[0] = (unsigned short)(v[j].x & 0xffff); d[136] = (unsigned short)(v[j].x >> 16); d[2 * 136] = (unsigned short)(v[j].y & 0xffff); d[3 * 136] = (unsigned short)(v[j].y >> 16);
;         d[4 * 136] = (unsigned short)(v[j].z & 0xffff); d[5 * 136] = (unsigned short)(v[j].z >> 16); d[6 * 136] = (unsigned short)(v[j].w & 0xffff); d[7 * 136] = (unsigned short)(v[j].w >> 16);
;     }
;     __syncthreads();
; #pragma unroll
;     for (int j = 0; j < 4; ++j) {
;         const int c = tid + j * NTHREADS, col = c >> 4, ch = c & 15;
;         const u32x4 w = *(const LAS u32x4*)(Lt + col * 136 + ((ch * 8) ^ (((col >> 3) & 15) << 3)));
;         *(u32x4*)(destrow(col) + ch * 8) = w;
;     }
.LBB0_373:
	s_and_b64 vcc, exec, s[0:1]
	s_mov_b64 s[0:1], -1
	s_waitcnt vmcnt(4)
	ds_write_b16 v67, v192
	ds_write_b16_d16_hi v67, v192 offset:272
	ds_write_b16 v67, v193 offset:544
	ds_write_b16_d16_hi v67, v193 offset:816
	ds_write_b16 v67, v194 offset:1088
	ds_write_b16_d16_hi v67, v194 offset:1360
	ds_write_b16 v67, v195 offset:1632
	ds_write_b16_d16_hi v67, v195 offset:1904
	ds_write_b16 v71, v196
	ds_write_b16_d16_hi v71, v196 offset:272
	ds_write_b16 v71, v197 offset:544
	ds_write_b16_d16_hi v71, v197 offset:816
	ds_write_b16 v71, v198 offset:1088
	ds_write_b16_d16_hi v71, v198 offset:1360
	ds_write_b16 v71, v199 offset:1632
	ds_write_b16_d16_hi v71, v199 offset:1904
	ds_write_b16 v77, v200
	ds_write_b16_d16_hi v77, v200 offset:272
	ds_write_b16 v77, v201 offset:544
	ds_write_b16_d16_hi v77, v201 offset:816
	ds_write_b16 v77, v202 offset:1088
	ds_write_b16_d16_hi v77, v202 offset:1360
	ds_write_b16 v77, v203 offset:1632
	ds_write_b16_d16_hi v77, v203 offset:1904
	ds_write_b16 v106, v204
	ds_write_b16_d16_hi v106, v204 offset:272
	ds_write_b16 v106, v205 offset:544
	ds_write_b16_d16_hi v106, v205 offset:816
	ds_write_b16 v106, v206 offset:1088
	ds_write_b16_d16_hi v106, v206 offset:1360
	ds_write_b16 v106, v207 offset:1632
	ds_write_b16_d16_hi v106, v207 offset:1904
	s_waitcnt lgkmcnt(0)
	s_cbranch_vccnz .LBB0_375
	s_or_b32 s0, s10, 0xc0
	s_barrier
	ds_read_b128 v[8:11], v107
	v_or_b32_e32 v186, s0, v58
	v_lshlrev_b64 v[12:13], 10, v[186:187]
	v_lshl_add_u64 v[6:7], v[6:7], 0, v[12:13]
	ds_read_b128 v[12:15], v108
	v_or_b32_e32 v186, s0, v62
	s_waitcnt lgkmcnt(1)
	global_store_dwordx4 v[6:7], v[8:11], off
	v_lshlrev_b64 v[6:7], 10, v[186:187]
	v_lshl_add_u64 v[4:5], v[4:5], 0, v[6:7]
	s_waitcnt lgkmcnt(0)
	global_store_dwordx4 v[4:5], v[12:15], off
	ds_read_b128 v[4:7], v109
	v_or_b32_e32 v186, s0, v66
	v_lshlrev_b64 v[8:9], 10, v[186:187]
	v_lshl_add_u64 v[2:3], v[2:3], 0, v[8:9]
	ds_read_b128 v[8:11], v110
	v_or_b32_e32 v186, s0, v70
	s_waitcnt lgkmcnt(1)
	global_store_dwordx4 v[2:3], v[4:7], off
	v_lshlrev_b64 v[2:3], 10, v[186:187]
	v_lshl_add_u64 v[0:1], v[0:1], 0, v[2:3]
	s_mov_b64 s[0:1], 0
	s_waitcnt lgkmcnt(0)
	global_store_dwordx4 v[0:1], v[8:11], off
	s_barrier
